# NSA half-row max exchange via v_permlane32_swap instead of ds_bpermute + LDS wait
# speedup vs baseline: 1.0011x; 1.0011x over previous
; DI float fexp2(float x) { return __builtin_amdgcn_exp2f(x); }
; DI float half_max(float v) { return fmaxf(v, __shfl_xor(v, 32)); }
; DI void flash_pv(FState& st, f32x16& p0, f32x16& p1, bool rowon, const LAS unsigned char* vb, int lane) {
;     float mx = fmaxf(p0[0], p1[0]);
; #pragma unroll
;     for (int r = 1; r < 16; ++r) asm("v_max3_f32 %0, %1, %2, %3" : "=v"(mx) : "v"(mx), "v"(p0[r]), "v"(p1[r]));
;     mx = half_max(mx);
;     mx = rowon ? mx : NINF;
;     const bool upd = mx > st.m + THR_RAW;
;     if (__any(upd)) {
;         const float mn = upd ? mx : st.m;
;         const float alpha = upd ? fexp2((st.m - mn) * SM_C) : 1.0f;
;         st.m = mn; st.l *= alpha;
; #pragma unroll
;         for (int r = 0; r < 16; ++r) { st.o0[r] *= alpha; st.o1[r] *= alpha; }
;     }
.LBB0_753:
	v_max_f32_e32 v2, v82, v82
	v_max_f32_e32 v4, v98, v98
	v_max_f32_e32 v2, v4, v2
	v_max3_f32 v2, v2, v99, v83
	v_and_b32_e32 v5, 64, v198
	v_max3_f32 v2, v2, v100, v84
	v_xor_b32_e32 v4, 32, v198
	v_max3_f32 v2, v2, v101, v85
	v_add_u32_e32 v5, 64, v5
	v_max3_f32 v2, v2, v102, v86
	v_cmp_lt_i32_e32 vcc, v4, v5
	v_max3_f32 v2, v2, v103, v87
	v_max3_f32 v2, v2, v104, v88
	v_max3_f32 v2, v2, v105, v89
	v_cndmask_b32_e32 v4, v198, v4, vcc
	v_max3_f32 v2, v2, v106, v90
	v_lshlrev_b32_e32 v215, 2, v4
	v_max3_f32 v2, v2, v107, v91
	v_max3_f32 v2, v2, v108, v92
	v_max3_f32 v2, v2, v109, v93
	v_max3_f32 v2, v2, v110, v94
	v_max3_f32 v2, v2, v111, v95
	v_max3_f32 v2, v2, v112, v96
	v_max3_f32 v2, v2, v113, v97
	v_mov_b32_e32 v4, v2
	s_nop 1
	v_permlane32_swap_b32_e32 v4, v2
	s_nop 0
	v_max_f32_e32 v2, v2, v4
	v_cndmask_b32_e64 v2, v186, v2, s[8:9]
	v_add_f32_e32 v4, 0x42317218, v216
	v_cmp_gt_f32_e32 vcc, v2, v4
	s_cbranch_vccz .LBB0_755
	s_nop 0
	v_cndmask_b32_e32 v4, v216, v2, vcc
	v_sub_f32_e32 v2, v216, v4
	v_mul_f32_e32 v2, 0x3e38aa3b, v2
	v_exp_f32_e32 v2, v2
	v_mov_b32_e32 v216, v4
	v_cndmask_b32_e32 v2, 1.0, v2, vcc
	v_mul_f32_e32 v214, v214, v2
	v_pk_mul_f32 v[80:81], v[80:81], v[2:3] op_sel_hi:[1,0]
	v_pk_mul_f32 v[78:79], v[78:79], v[2:3] op_sel_hi:[1,0]
	v_pk_mul_f32 v[76:77], v[76:77], v[2:3] op_sel_hi:[1,0]
	v_pk_mul_f32 v[74:75], v[74:75], v[2:3] op_sel_hi:[1,0]
	v_pk_mul_f32 v[72:73], v[72:73], v[2:3] op_sel_hi:[1,0]
	v_pk_mul_f32 v[70:71], v[70:71], v[2:3] op_sel_hi:[1,0]
	v_pk_mul_f32 v[68:69], v[68:69], v[2:3] op_sel_hi:[1,0]
	v_pk_mul_f32 v[66:67], v[66:67], v[2:3] op_sel_hi:[1,0]
	v_pk_mul_f32 v[64:65], v[64:65], v[2:3] op_sel_hi:[1,0]
	v_pk_mul_f32 v[62:63], v[62:63], v[2:3] op_sel_hi:[1,0]
	v_pk_mul_f32 v[60:61], v[60:61], v[2:3] op_sel_hi:[1,0]
	v_pk_mul_f32 v[58:59], v[58:59], v[2:3] op_sel_hi:[1,0]
	v_pk_mul_f32 v[56:57], v[56:57], v[2:3] op_sel_hi:[1,0]
	v_pk_mul_f32 v[54:55], v[54:55], v[2:3] op_sel_hi:[1,0]
	v_pk_mul_f32 v[52:53], v[52:53], v[2:3] op_sel_hi:[1,0]
	v_pk_mul_f32 v[50:51], v[50:51], v[2:3] op_sel_hi:[1,0]

; DI float fexp2(float x) { return __builtin_amdgcn_exp2f(x); }
; DI float half_max(float v) { return fmaxf(v, __shfl_xor(v, 32)); }
; DI void flash_pv(FState& st, f32x16& p0, f32x16& p1, bool rowon, const LAS unsigned char* vb, int lane) {
;     float mx = fmaxf(p0[0], p1[0]);
; #pragma unroll
;     for (int r = 1; r < 16; ++r) asm("v_max3_f32 %0, %1, %2, %3" : "=v"(mx) : "v"(mx), "v"(p0[r]), "v"(p1[r]));
;     mx = half_max(mx);
;     mx = rowon ? mx : NINF;
;     const bool upd = mx > st.m + THR_RAW;
;     if (__any(upd)) {
;         const float mn = upd ? mx : st.m;
;         const float alpha = upd ? fexp2((st.m - mn) * SM_C) : 1.0f;
;         st.m = mn; st.l *= alpha;
; #pragma unroll
;         for (int r = 0; r < 16; ++r) { st.o0[r] *= alpha; st.o1[r] *= alpha; }
;     }
.LBB0_772:
	v_max_f32_e32 v2, v82, v82
	v_max_f32_e32 v4, v98, v98
	v_max_f32_e32 v2, v4, v2
	v_max3_f32 v2, v2, v99, v83
	v_max3_f32 v2, v2, v100, v84
	v_max3_f32 v2, v2, v101, v85
	v_max3_f32 v2, v2, v102, v86
	v_max3_f32 v2, v2, v103, v87
	v_max3_f32 v2, v2, v104, v88
	v_max3_f32 v2, v2, v105, v89
	v_max3_f32 v2, v2, v106, v90
	v_max3_f32 v2, v2, v107, v91
	v_max3_f32 v2, v2, v108, v92
	v_max3_f32 v2, v2, v109, v93
	v_max3_f32 v2, v2, v110, v94
	v_max3_f32 v2, v2, v111, v95
	v_max3_f32 v2, v2, v112, v96
	v_max3_f32 v2, v2, v113, v97
	v_mov_b32_e32 v4, v2
	s_nop 1
	v_permlane32_swap_b32_e32 v4, v2
	s_nop 0
	v_max_f32_e32 v2, v2, v4
	v_cndmask_b32_e64 v2, v186, v2, s[8:9]
	v_add_f32_e32 v4, 0x42317218, v216
	v_cmp_gt_f32_e32 vcc, v2, v4
	s_cbranch_vccz .LBB0_774
	s_nop 0
	v_cndmask_b32_e32 v4, v216, v2, vcc
	v_sub_f32_e32 v2, v216, v4
	v_mul_f32_e32 v2, 0x3e38aa3b, v2
	v_exp_f32_e32 v2, v2
	v_mov_b32_e32 v216, v4
	v_cndmask_b32_e32 v2, 1.0, v2, vcc
	v_mul_f32_e32 v214, v214, v2
	v_pk_mul_f32 v[80:81], v[80:81], v[2:3] op_sel_hi:[1,0]
	v_pk_mul_f32 v[78:79], v[78:79], v[2:3] op_sel_hi:[1,0]
	v_pk_mul_f32 v[76:77], v[76:77], v[2:3] op_sel_hi:[1,0]
	v_pk_mul_f32 v[74:75], v[74:75], v[2:3] op_sel_hi:[1,0]
	v_pk_mul_f32 v[72:73], v[72:73], v[2:3] op_sel_hi:[1,0]
	v_pk_mul_f32 v[70:71], v[70:71], v[2:3] op_sel_hi:[1,0]
	v_pk_mul_f32 v[68:69], v[68:69], v[2:3] op_sel_hi:[1,0]
	v_pk_mul_f32 v[66:67], v[66:67], v[2:3] op_sel_hi:[1,0]
	v_pk_mul_f32 v[64:65], v[64:65], v[2:3] op_sel_hi:[1,0]
	v_pk_mul_f32 v[62:63], v[62:63], v[2:3] op_sel_hi:[1,0]
	v_pk_mul_f32 v[60:61], v[60:61], v[2:3] op_sel_hi:[1,0]
	v_pk_mul_f32 v[58:59], v[58:59], v[2:3] op_sel_hi:[1,0]
	v_pk_mul_f32 v[56:57], v[56:57], v[2:3] op_sel_hi:[1,0]
	v_pk_mul_f32 v[54:55], v[54:55], v[2:3] op_sel_hi:[1,0]
	v_pk_mul_f32 v[52:53], v[52:53], v[2:3] op_sel_hi:[1,0]
	v_pk_mul_f32 v[50:51], v[50:51], v[2:3] op_sel_hi:[1,0]
